# grid barrier: invalidate issued after the leader decision (leader: behind its TOP add) so the release write-back does not queue behind it
# baseline (speedup 1.0000x reference)
; __device__ __forceinline__ unsigned xb_ld(unsigned* p)              { return __hip_atomic_load(p, __ATOMIC_RELAXED, __HIP_MEMORY_SCOPE_AGENT); }
; __device__ __forceinline__ unsigned xb_add(unsigned* p, unsigned v) { return __hip_atomic_fetch_add(p, v, __ATOMIC_RELAXED, __HIP_MEMORY_SCOPE_AGENT); }
; #define XB_SPIN(cond, bar) do { unsigned _sp = 0; while (cond) { __builtin_amdgcn_s_sleep(1); \
;     if ((++_sp & 255u) == 0u) { if (xb_ld(&(bar)[XB_TMO])) break; if (_sp > XB_SPIN_CAP) { atomicAdd(&(bar)[XB_TMO], 1u); break; } } } } while (0)
; __device__ __forceinline__ void xcd_barrier(const XcdBarrier& b) {
;     ...
;         const unsigned old = xb_add(&bar[XB_XSUB(b.x)], 1u);
;         const unsigned gen = old / nloc;
;         if (old + 1u == (gen + 1u) * nloc) {
;             __builtin_amdgcn_fence(__ATOMIC_RELEASE, "agent");
;             asm volatile("s_waitcnt vmcnt(0)" ::: "memory");
;             const unsigned og = xb_add(&bar[XB_TOP], 1u);
;             const unsigned tg = og / nx;
;             if (og + 1u == (tg + 1u) * nx) xb_add(&bar[XB_TOPGEN], 1u);
;             else XB_SPIN(xb_ld(&bar[XB_TOPGEN]) == tg, bar);
;             __builtin_amdgcn_fence(__ATOMIC_ACQUIRE, "agent");
;             xb_add(&bar[XB_XGEN(b.x)], 1u);
;             asm volatile("s_waitcnt vmcnt(0)" ::: "memory");
;         } else {
;             XB_SPIN(xb_ld(&bar[XB_XGEN(b.x)]) == gen, bar);
;             __builtin_amdgcn_fence(__ATOMIC_ACQUIRE, "agent");
;             asm volatile("s_waitcnt vmcnt(0)" ::: "memory");
.LBB0_1396:
	s_or_b64 exec, exec, s[40:41]
	v_cvt_f32_u32_e32 v4, v2
	s_waitcnt vmcnt(0)
	v_readfirstlane_b32 s29, v3
	v_sub_u32_e32 v3, 0, v2
	v_rcp_iflag_f32_e32 v4, v4
	v_add_u32_e32 v5, s29, v1
	v_mul_f32_e32 v4, 0x4f7ffffe, v4
	v_cvt_u32_f32_e32 v4, v4
	v_mul_lo_u32 v1, v3, v4
	v_mul_hi_u32 v1, v4, v1
	v_add_u32_e32 v1, v4, v1
	v_mul_hi_u32 v1, v5, v1
	v_mul_lo_u32 v3, v1, v2
	v_sub_u32_e32 v3, v5, v3
	v_add_u32_e32 v4, 1, v1
	v_cmp_ge_u32_e32 vcc, v3, v2
	s_nop 1
	v_cndmask_b32_e32 v1, v1, v4, vcc
	v_sub_u32_e32 v4, v3, v2
	v_cndmask_b32_e32 v3, v3, v4, vcc
	v_add_u32_e32 v4, 1, v1
	v_cmp_ge_u32_e32 vcc, v3, v2
	v_add_u32_e32 v3, 1, v5
	s_nop 0
	v_cndmask_b32_e32 v1, v1, v4, vcc
	v_mul_lo_u32 v4, v2, v1
	v_add_u32_e32 v2, v4, v2
	v_cmp_ne_u32_e32 vcc, v3, v2
	s_and_saveexec_b64 s[34:35], vcc
	s_xor_b64 s[40:41], exec, s[34:35]
	s_cbranch_execz .LBB0_1410
	v_add_u32_e32 v4, 1, v1
	v_mul_lo_u32 v4, v4, v0
	buffer_inv sc1
	v_readlane_b32 s34, v252, 40
	v_readlane_b32 s35, v252, 41
	s_waitcnt lgkmcnt(0)
	s_nop 3
	global_load_dword v0, v65, s[34:35] sc1
	s_waitcnt vmcnt(0)
	v_cmp_lt_u32_e32 vcc, v0, v4
	s_and_saveexec_b64 s[42:43], vcc
	s_cbranch_execz .LBB0_1409
	s_mov_b32 s29, 1
	s_mov_b64 s[44:45], 0
	s_branch .LBB0_1400

; __device__ __forceinline__ unsigned xb_ld(unsigned* p)              { return __hip_atomic_load(p, __ATOMIC_RELAXED, __HIP_MEMORY_SCOPE_AGENT); }
; __device__ __forceinline__ unsigned xb_add(unsigned* p, unsigned v) { return __hip_atomic_fetch_add(p, v, __ATOMIC_RELAXED, __HIP_MEMORY_SCOPE_AGENT); }
; #define XB_SPIN(cond, bar) do { unsigned _sp = 0; while (cond) { __builtin_amdgcn_s_sleep(1); \
;     if ((++_sp & 255u) == 0u) { if (xb_ld(&(bar)[XB_TMO])) break; if (_sp > XB_SPIN_CAP) { atomicAdd(&(bar)[XB_TMO], 1u); break; } } } } while (0)
; __device__ __forceinline__ void xcd_barrier(const XcdBarrier& b) {
;     ...
;         const unsigned old = xb_add(&bar[XB_XSUB(b.x)], 1u);
;         const unsigned gen = old / nloc;
;         if (old + 1u == (gen + 1u) * nloc) {
;             __builtin_amdgcn_fence(__ATOMIC_RELEASE, "agent");
;             asm volatile("s_waitcnt vmcnt(0)" ::: "memory");
;             const unsigned og = xb_add(&bar[XB_TOP], 1u);
;             const unsigned tg = og / nx;
;             if (og + 1u == (tg + 1u) * nx) xb_add(&bar[XB_TOPGEN], 1u);
;             else XB_SPIN(xb_ld(&bar[XB_TOPGEN]) == tg, bar);
;             __builtin_amdgcn_fence(__ATOMIC_ACQUIRE, "agent");
;             xb_add(&bar[XB_XGEN(b.x)], 1u);
;             asm volatile("s_waitcnt vmcnt(0)" ::: "memory");
;         } else {
;             XB_SPIN(xb_ld(&bar[XB_XGEN(b.x)]) == gen, bar);
;             __builtin_amdgcn_fence(__ATOMIC_ACQUIRE, "agent");
;             asm volatile("s_waitcnt vmcnt(0)" ::: "memory");
.LBB0_1413:
	s_or_b64 exec, exec, s[42:43]
	buffer_inv sc1
	s_waitcnt vmcnt(0)
	v_readfirstlane_b32 s29, v2
	v_cvt_f32_u32_e32 v2, v0
	v_sub_u32_e32 v3, 0, v0
	v_add_u32_e32 v1, s29, v1
	v_readlane_b32 s34, v252, 42
	v_rcp_iflag_f32_e32 v2, v2
	v_readlane_b32 s35, v252, 43
	s_mov_b64 s[42:43], -1
	v_mul_f32_e32 v2, 0x4f7ffffe, v2
	v_cvt_u32_f32_e32 v2, v2
	v_mul_lo_u32 v3, v3, v2
	v_mul_hi_u32 v3, v2, v3
	v_add_u32_e32 v2, v2, v3
	v_mul_hi_u32 v2, v1, v2
	v_mul_lo_u32 v3, v2, v0
	v_sub_u32_e32 v3, v1, v3
	v_cmp_ge_u32_e32 vcc, v3, v0
	v_add_u32_e32 v4, 1, v2
	v_add_u32_e32 v1, 1, v1
	v_cndmask_b32_e32 v2, v2, v4, vcc
	v_sub_u32_e32 v4, v3, v0
	v_cndmask_b32_e32 v3, v3, v4, vcc
	v_cmp_ge_u32_e32 vcc, v3, v0
	v_add_u32_e32 v3, 1, v2
	s_nop 0
	v_cndmask_b32_e32 v2, v2, v3, vcc
	v_mul_lo_u32 v3, v0, v2
	v_add_u32_e32 v0, v3, v0
	v_mov_b32_e32 v4, v0
	v_cmp_ne_u32_e32 vcc, v1, v0
	v_mov_b64_e32 v[0:1], s[34:35]
	s_and_saveexec_b64 s[40:41], vcc
	s_cbranch_execz .LBB0_1426
	v_readlane_b32 s34, v252, 40
	v_readlane_b32 s35, v252, 41
	s_mov_b64 s[44:45], 0
	s_nop 3
	global_load_dword v0, v65, s[34:35] sc1
	s_waitcnt vmcnt(0)
	v_cmp_lt_u32_e32 vcc, v0, v4
	s_and_saveexec_b64 s[42:43], vcc
	s_cbranch_execz .LBB0_1425
	s_mov_b32 s29, 1
	s_branch .LBB0_1417

; __device__ __forceinline__ unsigned xb_ld(unsigned* p)              { return __hip_atomic_load(p, __ATOMIC_RELAXED, __HIP_MEMORY_SCOPE_AGENT); }
; __device__ __forceinline__ unsigned xb_add(unsigned* p, unsigned v) { return __hip_atomic_fetch_add(p, v, __ATOMIC_RELAXED, __HIP_MEMORY_SCOPE_AGENT); }
; #define XB_SPIN(cond, bar) do { unsigned _sp = 0; while (cond) { __builtin_amdgcn_s_sleep(1); \
;     if ((++_sp & 255u) == 0u) { if (xb_ld(&(bar)[XB_TMO])) break; if (_sp > XB_SPIN_CAP) { atomicAdd(&(bar)[XB_TMO], 1u); break; } } } } while (0)
; __device__ __forceinline__ void xcd_barrier(const XcdBarrier& b) {
;     ...
;         const unsigned old = xb_add(&bar[XB_XSUB(b.x)], 1u);
;         const unsigned gen = old / nloc;
;         if (old + 1u == (gen + 1u) * nloc) {
;             __builtin_amdgcn_fence(__ATOMIC_RELEASE, "agent");
;             asm volatile("s_waitcnt vmcnt(0)" ::: "memory");
;             const unsigned og = xb_add(&bar[XB_TOP], 1u);
;             const unsigned tg = og / nx;
;             if (og + 1u == (tg + 1u) * nx) xb_add(&bar[XB_TOPGEN], 1u);
;             else XB_SPIN(xb_ld(&bar[XB_TOPGEN]) == tg, bar);
;             __builtin_amdgcn_fence(__ATOMIC_ACQUIRE, "agent");
;             xb_add(&bar[XB_XGEN(b.x)], 1u);
;             asm volatile("s_waitcnt vmcnt(0)" ::: "memory");
;         } else {
;             XB_SPIN(xb_ld(&bar[XB_XGEN(b.x)]) == gen, bar);
;             __builtin_amdgcn_fence(__ATOMIC_ACQUIRE, "agent");
;             asm volatile("s_waitcnt vmcnt(0)" ::: "memory");
.LBB0_1451:
	s_or_b64 exec, exec, s[38:39]
	v_cvt_f32_u32_e32 v4, v2
	s_waitcnt vmcnt(0)
	v_readfirstlane_b32 s29, v3
	v_sub_u32_e32 v3, 0, v2
	v_rcp_iflag_f32_e32 v4, v4
	v_add_u32_e32 v5, s29, v1
	v_mul_f32_e32 v4, 0x4f7ffffe, v4
	v_cvt_u32_f32_e32 v4, v4
	v_mul_lo_u32 v1, v3, v4
	v_mul_hi_u32 v1, v4, v1
	v_add_u32_e32 v1, v4, v1
	v_mul_hi_u32 v1, v5, v1
	v_mul_lo_u32 v3, v1, v2
	v_sub_u32_e32 v3, v5, v3
	v_add_u32_e32 v4, 1, v1
	v_cmp_ge_u32_e32 vcc, v3, v2
	s_nop 1
	v_cndmask_b32_e32 v1, v1, v4, vcc
	v_sub_u32_e32 v4, v3, v2
	v_cndmask_b32_e32 v3, v3, v4, vcc
	v_add_u32_e32 v4, 1, v1
	v_cmp_ge_u32_e32 vcc, v3, v2
	v_add_u32_e32 v3, 1, v5
	s_nop 0
	v_cndmask_b32_e32 v1, v1, v4, vcc
	v_mul_lo_u32 v4, v2, v1
	v_add_u32_e32 v2, v4, v2
	v_cmp_ne_u32_e32 vcc, v3, v2
	s_and_saveexec_b64 s[34:35], vcc
	s_xor_b64 s[38:39], exec, s[34:35]
	s_cbranch_execz .LBB0_1465
	v_add_u32_e32 v4, 1, v1
	v_mul_lo_u32 v4, v4, v0
	buffer_inv sc1
	v_readlane_b32 s34, v252, 40
	v_readlane_b32 s35, v252, 41
	s_waitcnt lgkmcnt(0)
	s_nop 3
	global_load_dword v0, v65, s[34:35] sc1
	s_waitcnt vmcnt(0)
	v_cmp_lt_u32_e32 vcc, v0, v4
	s_and_saveexec_b64 s[40:41], vcc
	s_cbranch_execz .LBB0_1464
	s_mov_b32 s29, 1
	s_mov_b64 s[42:43], 0
	s_branch .LBB0_1455

; __device__ __forceinline__ unsigned xb_ld(unsigned* p)              { return __hip_atomic_load(p, __ATOMIC_RELAXED, __HIP_MEMORY_SCOPE_AGENT); }
; __device__ __forceinline__ unsigned xb_add(unsigned* p, unsigned v) { return __hip_atomic_fetch_add(p, v, __ATOMIC_RELAXED, __HIP_MEMORY_SCOPE_AGENT); }
; #define XB_SPIN(cond, bar) do { unsigned _sp = 0; while (cond) { __builtin_amdgcn_s_sleep(1); \
;     if ((++_sp & 255u) == 0u) { if (xb_ld(&(bar)[XB_TMO])) break; if (_sp > XB_SPIN_CAP) { atomicAdd(&(bar)[XB_TMO], 1u); break; } } } } while (0)
; __device__ __forceinline__ void xcd_barrier(const XcdBarrier& b) {
;     ...
;         const unsigned old = xb_add(&bar[XB_XSUB(b.x)], 1u);
;         const unsigned gen = old / nloc;
;         if (old + 1u == (gen + 1u) * nloc) {
;             __builtin_amdgcn_fence(__ATOMIC_RELEASE, "agent");
;             asm volatile("s_waitcnt vmcnt(0)" ::: "memory");
;             const unsigned og = xb_add(&bar[XB_TOP], 1u);
;             const unsigned tg = og / nx;
;             if (og + 1u == (tg + 1u) * nx) xb_add(&bar[XB_TOPGEN], 1u);
;             else XB_SPIN(xb_ld(&bar[XB_TOPGEN]) == tg, bar);
;             __builtin_amdgcn_fence(__ATOMIC_ACQUIRE, "agent");
;             xb_add(&bar[XB_XGEN(b.x)], 1u);
;             asm volatile("s_waitcnt vmcnt(0)" ::: "memory");
;         } else {
;             XB_SPIN(xb_ld(&bar[XB_XGEN(b.x)]) == gen, bar);
;             __builtin_amdgcn_fence(__ATOMIC_ACQUIRE, "agent");
;             asm volatile("s_waitcnt vmcnt(0)" ::: "memory");
.LBB0_1468:
	s_or_b64 exec, exec, s[40:41]
	buffer_inv sc1
	s_waitcnt vmcnt(0)
	v_readfirstlane_b32 s29, v2
	v_cvt_f32_u32_e32 v2, v0
	v_sub_u32_e32 v3, 0, v0
	v_add_u32_e32 v1, s29, v1
	v_readlane_b32 s34, v252, 42
	v_rcp_iflag_f32_e32 v2, v2
	v_readlane_b32 s35, v252, 43
	s_mov_b64 s[40:41], -1
	v_mul_f32_e32 v2, 0x4f7ffffe, v2
	v_cvt_u32_f32_e32 v2, v2
	v_mul_lo_u32 v3, v3, v2
	v_mul_hi_u32 v3, v2, v3
	v_add_u32_e32 v2, v2, v3
	v_mul_hi_u32 v2, v1, v2
	v_mul_lo_u32 v3, v2, v0
	v_sub_u32_e32 v3, v1, v3
	v_cmp_ge_u32_e32 vcc, v3, v0
	v_add_u32_e32 v4, 1, v2
	v_add_u32_e32 v1, 1, v1
	v_cndmask_b32_e32 v2, v2, v4, vcc
	v_sub_u32_e32 v4, v3, v0
	v_cndmask_b32_e32 v3, v3, v4, vcc
	v_cmp_ge_u32_e32 vcc, v3, v0
	v_add_u32_e32 v3, 1, v2
	s_nop 0
	v_cndmask_b32_e32 v2, v2, v3, vcc
	v_mul_lo_u32 v3, v0, v2
	v_add_u32_e32 v0, v3, v0
	v_mov_b32_e32 v4, v0
	v_cmp_ne_u32_e32 vcc, v1, v0
	v_mov_b64_e32 v[0:1], s[34:35]
	s_and_saveexec_b64 s[38:39], vcc
	s_cbranch_execz .LBB0_1480
	v_readlane_b32 s34, v252, 40
	v_readlane_b32 s35, v252, 41
	s_mov_b64 s[42:43], 0
	s_nop 3
	global_load_dword v0, v65, s[34:35] sc1
	s_waitcnt vmcnt(0)
	v_cmp_lt_u32_e32 vcc, v0, v4
	s_and_saveexec_b64 s[40:41], vcc
	s_cbranch_execz .LBB0_1479
	s_mov_b32 s29, 1
	s_branch .LBB0_1472
